# speedup vs baseline: 1.0045x; 1.0017x over previous
; __device__ __forceinline__ unsigned xb_ld(unsigned* p)              { return __hip_atomic_load(p, __ATOMIC_RELAXED, __HIP_MEMORY_SCOPE_AGENT); }
; __device__ __forceinline__ unsigned xb_add(unsigned* p, unsigned v) { return __hip_atomic_fetch_add(p, v, __ATOMIC_RELAXED, __HIP_MEMORY_SCOPE_AGENT); }
; #define XB_SPIN(cond, bar) do { unsigned _sp = 0; while (cond) { __builtin_amdgcn_s_sleep(1); \
;     if ((++_sp & 255u) == 0u) { if (xb_ld(&(bar)[XB_TMO])) break; if (_sp > XB_SPIN_CAP) { atomicAdd(&(bar)[XB_TMO], 1u); break; } } } } while (0)
; __device__ __forceinline__ void xcd_barrier(const XcdBarrier& b) {
;     ...
;         const unsigned old = xb_add(&bar[XB_XSUB(b.x)], 1u);
;         const unsigned gen = old / nloc;
;         if (old + 1u == (gen + 1u) * nloc) {
;             __builtin_amdgcn_fence(__ATOMIC_RELEASE, "agent");
;             asm volatile("s_waitcnt vmcnt(0)" ::: "memory");
;             const unsigned og = xb_add(&bar[XB_TOP], 1u);
;             const unsigned tg = og / nx;
;             if (og + 1u == (tg + 1u) * nx) xb_add(&bar[XB_TOPGEN], 1u);
;             else XB_SPIN(xb_ld(&bar[XB_TOPGEN]) == tg, bar);
;             __builtin_amdgcn_fence(__ATOMIC_ACQUIRE, "agent");
;             xb_add(&bar[XB_XGEN(b.x)], 1u);
;             asm volatile("s_waitcnt vmcnt(0)" ::: "memory");
;         } else {
;             XB_SPIN(xb_ld(&bar[XB_XGEN(b.x)]) == gen, bar);
.LBB0_122:
	s_or_b64 exec, exec, s[22:23]
	v_cvt_f32_u32_e32 v4, v2
	s_waitcnt vmcnt(0)
	v_readfirstlane_b32 s2, v3
	v_sub_u32_e32 v3, 0, v2
	v_rcp_iflag_f32_e32 v4, v4
	v_add_u32_e32 v5, s2, v1
	v_mul_f32_e32 v4, 0x4f7ffffe, v4
	v_cvt_u32_f32_e32 v4, v4
	v_mul_lo_u32 v1, v3, v4
	v_mul_hi_u32 v1, v4, v1
	v_add_u32_e32 v1, v4, v1
	v_mul_hi_u32 v1, v5, v1
	v_mul_lo_u32 v3, v1, v2
	v_sub_u32_e32 v3, v5, v3
	v_add_u32_e32 v4, 1, v1
	v_sub_u32_e32 v6, v3, v2
	v_cmp_ge_u32_e32 vcc, v3, v2
	s_nop 1
	v_cndmask_b32_e32 v1, v1, v4, vcc
	v_cndmask_b32_e32 v3, v3, v6, vcc
	v_add_u32_e32 v4, 1, v1
	v_cmp_ge_u32_e32 vcc, v3, v2
	v_add_u32_e32 v3, 1, v5
	s_nop 0
	v_cndmask_b32_e32 v1, v1, v4, vcc
	v_mul_lo_u32 v4, v2, v1
	v_add_u32_e32 v2, v4, v2
	v_cmp_ne_u32_e32 vcc, v3, v2
	s_and_saveexec_b64 s[2:3], vcc
	s_xor_b64 s[22:23], exec, s[2:3]
	s_cbranch_execz .LBB0_136
	v_readlane_b32 s2, v253, 52
	v_readlane_b32 s3, v253, 53
	s_waitcnt lgkmcnt(0)
	s_nop 3
	global_load_dword v0, v65, s[2:3] sc1
	s_waitcnt vmcnt(0)
	v_cmp_eq_u32_e32 vcc, v0, v1
	s_and_saveexec_b64 s[28:29], vcc
	s_cbranch_execz .LBB0_135
	s_mov_b32 s2, 1
	s_mov_b64 s[36:37], 0
	s_branch .LBB0_126

; __device__ __forceinline__ unsigned xb_ld(unsigned* p)              { return __hip_atomic_load(p, __ATOMIC_RELAXED, __HIP_MEMORY_SCOPE_AGENT); }
; #define XB_SPIN(cond, bar) do { unsigned _sp = 0; while (cond) { __builtin_amdgcn_s_sleep(1); \
;     if ((++_sp & 255u) == 0u) { if (xb_ld(&(bar)[XB_TMO])) break; if (_sp > XB_SPIN_CAP) { atomicAdd(&(bar)[XB_TMO], 1u); break; } } } } while (0)
; __device__ __forceinline__ void xcd_barrier(const XcdBarrier& b) {
;     ...
;             XB_SPIN(xb_ld(&bar[XB_XGEN(b.x)]) == gen, bar);
.LBB0_130:
	v_readlane_b32 s42, v253, 52
	v_readlane_b32 s43, v253, 53
	s_add_i32 s2, s2, 1
	s_mov_b64 s[44:45], -1
	s_nop 2
	global_load_dword v0, v65, s[42:43] sc1
	s_waitcnt vmcnt(0)
	v_cmp_ne_u32_e32 vcc, v0, v1
	s_orn2_b64 s[42:43], vcc, exec
	s_branch .LBB0_125

; __device__ __forceinline__ unsigned xb_ld(unsigned* p)              { return __hip_atomic_load(p, __ATOMIC_RELAXED, __HIP_MEMORY_SCOPE_AGENT); }
; __device__ __forceinline__ unsigned xb_add(unsigned* p, unsigned v) { return __hip_atomic_fetch_add(p, v, __ATOMIC_RELAXED, __HIP_MEMORY_SCOPE_AGENT); }
; #define XB_SPIN(cond, bar) do { unsigned _sp = 0; while (cond) { __builtin_amdgcn_s_sleep(1); \
;     if ((++_sp & 255u) == 0u) { if (xb_ld(&(bar)[XB_TMO])) break; if (_sp > XB_SPIN_CAP) { atomicAdd(&(bar)[XB_TMO], 1u); break; } } } } while (0)
; __device__ __forceinline__ void xcd_barrier(const XcdBarrier& b) {
;     ...
;         const unsigned old = xb_add(&bar[XB_XSUB(b.x)], 1u);
;         const unsigned gen = old / nloc;
;         if (old + 1u == (gen + 1u) * nloc) {
;             __builtin_amdgcn_fence(__ATOMIC_RELEASE, "agent");
;             asm volatile("s_waitcnt vmcnt(0)" ::: "memory");
;             const unsigned og = xb_add(&bar[XB_TOP], 1u);
;             const unsigned tg = og / nx;
;             if (og + 1u == (tg + 1u) * nx) xb_add(&bar[XB_TOPGEN], 1u);
;             else XB_SPIN(xb_ld(&bar[XB_TOPGEN]) == tg, bar);
;             __builtin_amdgcn_fence(__ATOMIC_ACQUIRE, "agent");
;             xb_add(&bar[XB_XGEN(b.x)], 1u);
;             asm volatile("s_waitcnt vmcnt(0)" ::: "memory");
;         } else {
;             XB_SPIN(xb_ld(&bar[XB_XGEN(b.x)]) == gen, bar);
.LBB0_745:
	s_or_b64 exec, exec, s[22:23]
	v_cvt_f32_u32_e32 v4, v2
	s_waitcnt vmcnt(0)
	v_readfirstlane_b32 s2, v3
	v_sub_u32_e32 v3, 0, v2
	v_rcp_iflag_f32_e32 v4, v4
	v_add_u32_e32 v5, s2, v1
	v_mul_f32_e32 v4, 0x4f7ffffe, v4
	v_cvt_u32_f32_e32 v4, v4
	v_mul_lo_u32 v1, v3, v4
	v_mul_hi_u32 v1, v4, v1
	v_add_u32_e32 v1, v4, v1
	v_mul_hi_u32 v1, v5, v1
	v_mul_lo_u32 v3, v1, v2
	v_sub_u32_e32 v3, v5, v3
	v_add_u32_e32 v4, 1, v1
	v_cmp_ge_u32_e32 vcc, v3, v2
	s_nop 1
	v_cndmask_b32_e32 v1, v1, v4, vcc
	v_sub_u32_e32 v4, v3, v2
	v_cndmask_b32_e32 v3, v3, v4, vcc
	v_add_u32_e32 v4, 1, v1
	v_cmp_ge_u32_e32 vcc, v3, v2
	v_add_u32_e32 v3, 1, v5
	s_nop 0
	v_cndmask_b32_e32 v1, v1, v4, vcc
	v_mul_lo_u32 v4, v2, v1
	v_add_u32_e32 v2, v4, v2
	v_cmp_ne_u32_e32 vcc, v3, v2
	s_and_saveexec_b64 s[2:3], vcc
	s_xor_b64 s[22:23], exec, s[2:3]
	s_cbranch_execz .LBB0_759
	v_readlane_b32 s2, v253, 52
	v_readlane_b32 s3, v253, 53
	s_waitcnt lgkmcnt(0)
	s_nop 3
	global_load_dword v0, v65, s[2:3] sc1
	s_waitcnt vmcnt(0)
	v_cmp_eq_u32_e32 vcc, v0, v1
	s_and_saveexec_b64 s[28:29], vcc
	s_cbranch_execz .LBB0_758
	s_mov_b32 s2, 1
	s_mov_b64 s[36:37], 0
	s_branch .LBB0_749

; __device__ __forceinline__ unsigned xb_ld(unsigned* p)              { return __hip_atomic_load(p, __ATOMIC_RELAXED, __HIP_MEMORY_SCOPE_AGENT); }
; #define XB_SPIN(cond, bar) do { unsigned _sp = 0; while (cond) { __builtin_amdgcn_s_sleep(1); \
;     if ((++_sp & 255u) == 0u) { if (xb_ld(&(bar)[XB_TMO])) break; if (_sp > XB_SPIN_CAP) { atomicAdd(&(bar)[XB_TMO], 1u); break; } } } } while (0)
; __device__ __forceinline__ void xcd_barrier(const XcdBarrier& b) {
;     ...
;             XB_SPIN(xb_ld(&bar[XB_XGEN(b.x)]) == gen, bar);
.LBB0_753:
	v_readlane_b32 s40, v253, 52
	v_readlane_b32 s41, v253, 53
	s_add_i32 s2, s2, 1
	s_mov_b64 s[42:43], -1
	s_nop 2
	global_load_dword v0, v65, s[40:41] sc1
	s_waitcnt vmcnt(0)
	v_cmp_ne_u32_e32 vcc, v0, v1
	s_orn2_b64 s[40:41], vcc, exec
	s_branch .LBB0_748

; __device__ __forceinline__ unsigned xb_ld(unsigned* p)              { return __hip_atomic_load(p, __ATOMIC_RELAXED, __HIP_MEMORY_SCOPE_AGENT); }
; #define XB_SPIN(cond, bar) do { unsigned _sp = 0; while (cond) { __builtin_amdgcn_s_sleep(1); \
;     if ((++_sp & 255u) == 0u) { if (xb_ld(&(bar)[XB_TMO])) break; if (_sp > XB_SPIN_CAP) { atomicAdd(&(bar)[XB_TMO], 1u); break; } } } } while (0)
; __device__ __forceinline__ void xcd_barrier(const XcdBarrier& b) {
;     ...
;             XB_SPIN(xb_ld(&bar[XB_XGEN(b.x)]) == gen, bar);
.LBB0_1212:
	v_readlane_b32 s44, v253, 52
	v_readlane_b32 s45, v253, 53
	s_add_i32 s2, s2, 1
	s_mov_b64 s[46:47], -1
	s_nop 2
	global_load_dword v0, v65, s[44:45] sc1
	s_waitcnt vmcnt(0)
	v_cmp_ne_u32_e32 vcc, v0, v1
	s_orn2_b64 s[44:45], vcc, exec
	s_branch .LBB0_1207
